# speedup vs baseline: 1.0041x; 1.0041x over previous
; __device__ __forceinline__ f32x4 mfma16(bf16x8 a, bf16x8 b, f32x4 c) { return __builtin_amdgcn_mfma_f32_16x16x32_bf16(a, b, c, 0, 0, 0); }
; __device__ __forceinline__ void qk_tiles(f32x4 (&s)[8], const bf16_t* Ks, const bf16x8 (&qf)[4], int fr, int g, int tlo, int thi) {
;   __builtin_amdgcn_s_setprio(1);
; #pragma unroll
;   for (int T = 0; T < 8; ++T) {
;     s[T] = (f32x4){0.f, 0.f, 0.f, 0.f};
;     if (T >= tlo && T <= thi) {
; #pragma unroll
;       for (int kc = 0; kc < 4; ++kc) {
;         bf16x8 a = *(const bf16x8*)(Ks + (T * 16 + fr) * LROW + kc * 32 + g * 8);
;         s[T] = mfma16(a, qf[kc], s[T]);
;       }
;     }
;   }
;   __builtin_amdgcn_s_setprio(0);
; }
; __device__ __forceinline__ void sb_item(KParams p, int tb, int hd) {
;     ...
;   for (int j = i; j >= 0; --j) {
;     __syncthreads();
;     tile_st(kreg, Ks, tid); tile_st(vreg, Vts, tid);
;     __syncthreads();
;     {
;       const int ktok0 = (b * 64 + max(j - 1, 0)) * 128;
;       kreg = tile_ld(kbase + (size_t)ktok0 * NPROJ, NPROJ, tid);
;       vreg = tile_ld(vbase + ktok0, T_TOK, tid);
;     }
;     const bool wave_live = __any(carry >= -160.f) != 0;
;     const int thi = wave_live ? ((j == i) ? rt : 7) : -1;
;     if (thi >= 0) {
;       f32x4 s[8];
;       qk_tiles(s, Ks, qf, fr, g, 0, thi);
.LBB0_284:
	s_add_i32 s10, s13, 1
	s_cmp_lt_i32 s10, 0
	s_cbranch_scc1 .LBB0_293
	s_max_i32 s10, s13, 0
	s_add_i32 s14, s10, s82
	s_lshl_b32 s10, s14, 7
	v_mad_u64_u32 v[82:83], s[10:11], s10, v196, v[114:115]
	s_barrier
	s_waitcnt vmcnt(7)
	ds_write_b128 v176, v[18:21]
	s_waitcnt vmcnt(6)
	ds_write_b128 v176, v[22:25] offset:8704
	s_waitcnt vmcnt(5)
	ds_write_b128 v176, v[26:29] offset:17408
	s_waitcnt vmcnt(4)
	ds_write_b128 v176, v[34:37] offset:26112
	v_add_co_u32_e32 v22, vcc, s59, v82
	s_lshl_b32 s88, s14, 8
	s_nop 0
	v_addc_co_u32_e32 v23, vcc, 0, v83, vcc
	v_add_co_u32_e32 v26, vcc, s64, v82
	s_waitcnt vmcnt(3)
	ds_write_b128 v176, v[30:33] offset:34816
	s_waitcnt vmcnt(2)
	ds_write_b128 v176, v[38:41] offset:43520
	s_waitcnt vmcnt(1)
	ds_write_b128 v176, v[42:45] offset:52224
	s_waitcnt vmcnt(0)
	ds_write_b128 v176, v[46:49] offset:60928
	v_addc_co_u32_e32 v27, vcc, 0, v83, vcc
	v_add_co_u32_e32 v30, vcc, s65, v82
	v_lshl_add_u64 v[84:85], v[116:117], 0, s[88:89]
	s_nop 0
	v_addc_co_u32_e32 v31, vcc, 0, v83, vcc
	v_add_co_u32_e32 v38, vcc, 0x100000, v84
	s_waitcnt lgkmcnt(0)
	s_nop 0
	v_addc_co_u32_e32 v39, vcc, 0, v85, vcc
	v_add_co_u32_e32 v42, vcc, 0x200000, v84
	s_barrier
	s_nop 0
	v_addc_co_u32_e32 v43, vcc, 0, v85, vcc
	v_add_co_u32_e32 v46, vcc, 0x300000, v84
	s_nop 1
	v_addc_co_u32_e32 v47, vcc, 0, v85, vcc
	global_load_dwordx4 v[18:21], v[82:83], off offset:2048
	s_nop 0
	global_load_dwordx4 v[22:25], v[22:23], off offset:2048
	s_nop 0
	global_load_dwordx4 v[26:29], v[26:27], off offset:2048
	s_nop 0
	global_load_dwordx4 v[34:37], v[30:31], off offset:2048
	s_nop 0
	global_load_dwordx4 v[30:33], v[84:85], off
	s_nop 0
	global_load_dwordx4 v[38:41], v[38:39], off
	s_nop 0
	global_load_dwordx4 v[42:45], v[42:43], off
	v_cmp_le_f32_e32 vcc, s72, v118
	global_load_dwordx4 v[46:49], v[46:47], off
	s_cbranch_vccz .LBB0_287
	s_setprio 1
	ds_read_b128 v[82:85], v182
	ds_read_b128 v[86:89], v182 offset:64
	s_waitcnt lgkmcnt(1)
	v_mfma_f32_16x16x32_bf16 v[82:85], v[82:85], v[2:5], 0
	ds_read_b128 v[90:93], v182 offset:4416
	ds_read_b128 v[94:97], v182 offset:8768
	ds_read_b128 v[98:101], v182 offset:13120
	s_waitcnt lgkmcnt(3)
	v_mfma_f32_16x16x32_bf16 v[82:85], v[86:89], v[6:9], v[82:85]
	ds_read_b128 v[86:89], v182 offset:128
	ds_read_b128 v[104:107], v182 offset:17472
	ds_read_b128 v[108:111], v182 offset:21824
	s_waitcnt lgkmcnt(2)
	v_mfma_f32_16x16x32_bf16 v[82:85], v[86:89], v[10:13], v[82:85]
	ds_read_b128 v[86:89], v182 offset:192
	ds_read_b128 v[120:123], v182 offset:26176
	ds_read_b128 v[124:127], v182 offset:30528
	s_waitcnt lgkmcnt(2)
	v_mfma_f32_16x16x32_bf16 v[82:85], v[86:89], v[14:17], v[82:85]
	ds_read_b128 v[86:89], v182 offset:4352
	s_waitcnt lgkmcnt(0)
	v_mfma_f32_16x16x32_bf16 v[86:89], v[86:89], v[2:5], 0
	v_mfma_f32_16x16x32_bf16 v[86:89], v[90:93], v[6:9], v[86:89]
	ds_read_b128 v[90:93], v182 offset:4480
	s_waitcnt lgkmcnt(0)
	v_mfma_f32_16x16x32_bf16 v[86:89], v[90:93], v[10:13], v[86:89]
	ds_read_b128 v[90:93], v182 offset:4544
	s_waitcnt lgkmcnt(0)
	v_mfma_f32_16x16x32_bf16 v[86:89], v[90:93], v[14:17], v[86:89]
	ds_read_b128 v[90:93], v182 offset:8704
	s_waitcnt lgkmcnt(0)
	v_mfma_f32_16x16x32_bf16 v[90:93], v[90:93], v[2:5], 0
	v_mfma_f32_16x16x32_bf16 v[90:93], v[94:97], v[6:9], v[90:93]
	ds_read_b128 v[94:97], v182 offset:8832
	s_waitcnt lgkmcnt(0)
	v_mfma_f32_16x16x32_bf16 v[90:93], v[94:97], v[10:13], v[90:93]
	ds_read_b128 v[94:97], v182 offset:8896
	s_waitcnt lgkmcnt(0)
	v_mfma_f32_16x16x32_bf16 v[90:93], v[94:97], v[14:17], v[90:93]
	ds_read_b128 v[94:97], v182 offset:13056
	s_waitcnt lgkmcnt(0)
	v_mfma_f32_16x16x32_bf16 v[94:97], v[94:97], v[2:5], 0
	v_mfma_f32_16x16x32_bf16 v[94:97], v[98:101], v[6:9], v[94:97]
	ds_read_b128 v[98:101], v182 offset:13184
	s_waitcnt lgkmcnt(0)
	v_mfma_f32_16x16x32_bf16 v[94:97], v[98:101], v[10:13], v[94:97]
	ds_read_b128 v[98:101], v182 offset:13248
	s_waitcnt lgkmcnt(0)
	v_mfma_f32_16x16x32_bf16 v[96:99], v[98:101], v[14:17], v[94:97]
	ds_read_b128 v[100:103], v182 offset:17408
	s_waitcnt lgkmcnt(0)
	v_mfma_f32_16x16x32_bf16 v[100:103], v[100:103], v[2:5], 0
	v_mfma_f32_16x16x32_bf16 v[100:103], v[104:107], v[6:9], v[100:103]
	ds_read_b128 v[104:107], v182 offset:17536
	s_waitcnt lgkmcnt(0)
	v_mfma_f32_16x16x32_bf16 v[100:103], v[104:107], v[10:13], v[100:103]
	ds_read_b128 v[104:107], v182 offset:17600
	s_waitcnt lgkmcnt(0)
	v_mfma_f32_16x16x32_bf16 v[100:103], v[104:107], v[14:17], v[100:103]
	ds_read_b128 v[104:107], v182 offset:21760
	s_waitcnt lgkmcnt(0)
	v_mfma_f32_16x16x32_bf16 v[104:107], v[104:107], v[2:5], 0
	v_mfma_f32_16x16x32_bf16 v[104:107], v[108:111], v[6:9], v[104:107]
	ds_read_b128 v[108:111], v182 offset:21888
	s_waitcnt lgkmcnt(0)
	v_mfma_f32_16x16x32_bf16 v[104:107], v[108:111], v[10:13], v[104:107]
	ds_read_b128 v[108:111], v182 offset:21952
	s_waitcnt lgkmcnt(0)
	v_mfma_f32_16x16x32_bf16 v[104:107], v[108:111], v[14:17], v[104:107]
	ds_read_b128 v[108:111], v182 offset:26112
	s_waitcnt lgkmcnt(0)
	v_mfma_f32_16x16x32_bf16 v[108:111], v[108:111], v[2:5], 0
	v_mfma_f32_16x16x32_bf16 v[108:111], v[120:123], v[6:9], v[108:111]
	ds_read_b128 v[120:123], v182 offset:26240
	s_waitcnt lgkmcnt(0)
	v_mfma_f32_16x16x32_bf16 v[108:111], v[120:123], v[10:13], v[108:111]
	ds_read_b128 v[120:123], v182 offset:26304
	s_waitcnt lgkmcnt(0)
	v_mfma_f32_16x16x32_bf16 v[108:111], v[120:123], v[14:17], v[108:111]
	ds_read_b128 v[120:123], v182 offset:30464
	s_waitcnt lgkmcnt(0)
	v_mfma_f32_16x16x32_bf16 v[120:123], v[120:123], v[2:5], 0
	v_mfma_f32_16x16x32_bf16 v[120:123], v[124:127], v[6:9], v[120:123]
	ds_read_b128 v[124:127], v182 offset:30592
	s_waitcnt lgkmcnt(0)
; __device__ __forceinline__ float shfl_lane(float x, int src_lane) { return __int_as_float(__builtin_amdgcn_ds_bpermute(src_lane << 2, __float_as_int(x))); }
; __device__ __forceinline__ float ex2(float x) { return __builtin_amdgcn_exp2f(x); }
; __device__ __forceinline__ float lg2(float x) { return __builtin_amdgcn_logf(x); }
; __device__ __forceinline__ void sb_item(KParams p, int tb, int hd) {
;     ...
;       for (int T = 0; T < 8; ++T) {
;         if (T <= thi) {
; #pragma unroll
;           for (int r = 0; r < 4; ++r) {
;             const float z2 = s[T][r] * C2;
;             const float sp = fmaxf(z2, 0.f) + lg2(1.f + ex2(-fabsf(z2)));
;             l1[T][r] = -sp;
;             s[T][r] = z2 - sp;
;           }
;         }
;       }
;     ...
;       for (int T = 7; T >= 0; --T) {
;         if (T <= thi) {
;           const float x = (l1[T][0] + l1[T][1]) + (l1[T][2] + l1[T][3]);
;           float a = shfl_lane(x, (lane + 16) & 63); a = (g < 3) ? a : 0.f;
;           const float y1 = x + a;
;           float b2 = shfl_lane(y1, (lane + 32) & 63); b2 = (g < 2) ? b2 : 0.f;
;           const float incl = y1 + b2;
;           const float tt = shfl_lane(incl, fr);
	v_mfma_f32_16x16x32_bf16 v[120:123], v[124:127], v[10:13], v[120:123]
	ds_read_b128 v[124:127], v182 offset:30656
	s_waitcnt lgkmcnt(0)
	v_mfma_f32_16x16x32_bf16 v[184:187], v[124:127], v[14:17], v[120:123]
	s_setprio 0
	s_nop 3
	v_mul_f32_e32 v120, 0x3e0293ee, v83
	v_mul_f32_e32 v82, 0x3e0293ee, v82
	v_exp_f32_e64 v83, -|v120|
	v_exp_f32_e64 v94, -|v82|
	v_mul_f32_e32 v122, 0x3e0293ee, v84
	v_mul_f32_e32 v84, 0x3e0293ee, v85
	v_add_f32_e32 v83, 1.0, v83
	v_add_f32_e32 v94, 1.0, v94
	v_log_f32_e32 v133, v83
	v_exp_f32_e64 v83, -|v122|
	v_log_f32_e32 v135, v94
	v_exp_f32_e64 v94, -|v84|
	v_mul_f32_e32 v124, 0x3e0293ee, v86
	v_add_f32_e32 v83, 1.0, v83
	v_log_f32_e32 v134, v83
	v_add_f32_e32 v83, 1.0, v94
	v_log_f32_e32 v132, v83
	v_exp_f32_e64 v83, -|v124|
	v_mul_f32_e32 v126, 0x3e0293ee, v87
	v_max_f32_e32 v128, 0, v84
	v_exp_f32_e64 v84, -|v126|
	v_add_f32_e32 v83, 1.0, v83
	v_log_f32_e32 v143, v83
	v_mul_f32_e32 v88, 0x3e0293ee, v88
	v_add_f32_e32 v83, 1.0, v84
	v_log_f32_e32 v141, v83
	v_exp_f32_e64 v83, -|v88|
	v_mul_f32_e32 v84, 0x3e0293ee, v89
	v_exp_f32_e64 v94, -|v84|
	v_mul_f32_e32 v90, 0x3e0293ee, v90
	v_add_f32_e32 v83, 1.0, v83
	v_log_f32_e32 v142, v83
	v_add_f32_e32 v83, 1.0, v94
	v_log_f32_e32 v140, v83
	v_exp_f32_e64 v83, -|v90|
	v_mul_f32_e32 v136, 0x3e0293ee, v91
	v_max_f32_e32 v86, 0, v84
	v_exp_f32_e64 v84, -|v136|
	v_add_f32_e32 v83, 1.0, v83
	v_log_f32_e32 v153, v83
	v_mul_f32_e32 v92, 0x3e0293ee, v92
	v_add_f32_e32 v83, 1.0, v84
	v_log_f32_e32 v151, v83
	v_exp_f32_e64 v83, -|v92|
	v_mul_f32_e32 v84, 0x3e0293ee, v93
	v_exp_f32_e64 v91, -|v84|
	v_mul_f32_e32 v154, 0x3e0293ee, v96
	v_add_f32_e32 v83, 1.0, v83
	v_log_f32_e32 v152, v83
	v_add_f32_e32 v83, 1.0, v91
	v_log_f32_e32 v150, v83
	v_exp_f32_e64 v83, -|v154|
	v_mul_f32_e32 v156, 0x3e0293ee, v97
	v_max_f32_e32 v148, 0, v84
	v_exp_f32_e64 v84, -|v156|
	v_add_f32_e32 v83, 1.0, v83
	v_log_f32_e32 v167, v83
	v_mul_f32_e32 v158, 0x3e0293ee, v98
	v_add_f32_e32 v83, 1.0, v84
	v_log_f32_e32 v165, v83
	v_exp_f32_e64 v83, -|v158|
	v_mul_f32_e32 v84, 0x3e0293ee, v99
	v_exp_f32_e64 v91, -|v84|
	v_mul_f32_e32 v98, 0x3e0293ee, v100
	v_add_f32_e32 v83, 1.0, v83
	v_log_f32_e32 v166, v83
	v_add_f32_e32 v83, 1.0, v91
	v_log_f32_e32 v164, v83
	v_exp_f32_e64 v83, -|v98|
	v_mul_f32_e32 v100, 0x3e0293ee, v101
	v_max_f32_e32 v162, 0, v84
	v_exp_f32_e64 v84, -|v100|
	v_add_f32_e32 v83, 1.0, v83
	v_log_f32_e32 v146, v83
	v_mul_f32_e32 v102, 0x3e0293ee, v102
	v_add_f32_e32 v83, 1.0, v84
	v_log_f32_e32 v188, v83
	v_exp_f32_e64 v83, -|v102|
	v_mul_f32_e32 v84, 0x3e0293ee, v103
	v_exp_f32_e64 v91, -|v84|
	v_mul_f32_e32 v104, 0x3e0293ee, v104
	v_add_f32_e32 v83, 1.0, v83
	v_log_f32_e32 v147, v83
	v_add_f32_e32 v83, 1.0, v91
	v_log_f32_e32 v189, v83
	v_exp_f32_e64 v83, -|v104|
	v_mul_f32_e32 v168, 0x3e0293ee, v105
	v_max_f32_e32 v171, 0, v84
	v_exp_f32_e64 v84, -|v168|
	v_add_f32_e32 v83, 1.0, v83
	v_log_f32_e32 v200, v83
	v_mul_f32_e32 v106, 0x3e0293ee, v106
	v_add_f32_e32 v83, 1.0, v84
	v_log_f32_e32 v204, v83
	v_exp_f32_e64 v83, -|v106|
	v_mul_f32_e32 v84, 0x3e0293ee, v107
	v_exp_f32_e64 v91, -|v84|
	v_mul_f32_e32 v108, 0x3e0293ee, v108
	v_add_f32_e32 v83, 1.0, v83
	v_log_f32_e32 v201, v83
	v_add_f32_e32 v83, 1.0, v91
	v_log_f32_e32 v205, v83
	v_exp_f32_e64 v83, -|v108|
	v_mul_f32_e32 v206, 0x3e0293ee, v109
	v_max_f32_e32 v203, 0, v84
	v_exp_f32_e64 v84, -|v206|
	v_add_f32_e32 v83, 1.0, v83
	v_mul_f32_e32 v184, 0x3e0293ee, v184
	v_log_f32_e32 v208, v83
	v_add_f32_e32 v83, 1.0, v84
	v_exp_f32_e64 v84, -|v184|
	v_mul_f32_e32 v216, 0x3e0293ee, v185
	v_exp_f32_e64 v91, -|v216|
	v_mul_f32_e32 v186, 0x3e0293ee, v186
	v_add_f32_e32 v84, 1.0, v84
	v_log_f32_e32 v218, v84
	v_add_f32_e32 v84, 1.0, v91
	v_exp_f32_e64 v91, -|v186|
	v_mul_f32_e32 v101, 0x3e0293ee, v187
	v_exp_f32_e64 v105, -|v101|
	v_log_f32_e32 v222, v84
	v_add_f32_e32 v84, 1.0, v91
	v_log_f32_e32 v219, v84
	v_add_f32_e32 v84, 1.0, v105
	v_log_f32_e32 v223, v84
	v_max_f32_e32 v214, 0, v184
	v_max_f32_e32 v220, 0, v216
	v_max_f32_e32 v215, 0, v186
	v_max_f32_e32 v221, 0, v101
	v_pk_add_f32 v[214:215], v[214:215], v[218:219]
	v_pk_add_f32 v[218:219], v[220:221], v[222:223]
	v_mul_f32_e32 v110, 0x3e0293ee, v110
	v_pk_add_f32 v[220:221], v[218:219], v[214:215] neg_lo:[1,1] neg_hi:[1,1]
	v_log_f32_e32 v212, v83
	v_add_f32_e32 v84, v220, v221
	ds_bpermute_b32 v91, v178, v84
	v_exp_f32_e64 v83, -|v110|
	v_mov_b32_e32 v220, v215
	v_mov_b32_e32 v221, v219
	v_max_f32_e32 v96, 0, v108
	s_waitcnt lgkmcnt(0)
	v_cndmask_b32_e64 v91, v91, 0, s[4:5]
	v_add_f32_e32 v83, 1.0, v83
	v_add_f32_e32 v91, v91, v84
	v_log_f32_e32 v209, v83
	v_mul_f32_e32 v83, 0x3e0293ee, v111
	ds_bpermute_b32 v105, v179, v91
	v_exp_f32_e64 v101, -|v83|
	v_max_f32_e32 v211, 0, v83
	v_max_f32_e32 v210, 0, v206
	v_max_f32_e32 v97, 0, v110
	v_add_f32_e32 v83, 1.0, v101
	s_waitcnt lgkmcnt(0)
	v_cndmask_b32_e64 v101, 0, v105, s[6:7]
	v_add_f32_e32 v91, v101, v91
	v_sub_f32_e32 v84, v91, v84
	v_log_f32_e32 v213, v83
	v_fma_f32 v83, v187, s92, -v219
	v_add_f32_e32 v187, v118, v84
	v_add_f32_e32 v83, v83, v187
	v_pk_add_f32 v[186:187], v[186:187], v[220:221] neg_lo:[0,1] neg_hi:[0,1]
	v_mov_b32_e32 v219, v215
	v_mov_b32_e32 v217, v187
	v_add_f32_e32 v84, v186, v187
	v_pk_add_f32 v[186:187], v[216:217], v[218:219] neg_lo:[0,1] neg_hi:[0,1]
	v_mov_b32_e32 v215, v218
	v_add_f32_e32 v101, v186, v187
	v_mov_b32_e32 v185, v187
	v_pk_add_f32 v[186:187], v[96:97], v[208:209]
	v_pk_add_f32 v[208:209], v[210:211], v[212:213]
	v_exp_f32_e32 v83, v83
	v_pk_add_f32 v[96:97], v[208:209], v[186:187] neg_lo:[1,1] neg_hi:[1,1]
	v_exp_f32_e32 v84, v84
	v_pk_add_f32 v[210:211], v[96:97], v[96:97] op_sel:[0,1] op_sel_hi:[1,0]
	ds_bpermute_b32 v105, v178, v210
	v_pk_add_f32 v[96:97], v[184:185], v[214:215] neg_lo:[0,1] neg_hi:[0,1]
	ds_bpermute_b32 v184, v180, v91
	v_add_f32_e32 v96, v96, v97
	v_exp_f32_e32 v101, v101
	s_waitcnt lgkmcnt(1)
; __device__ __forceinline__ float shfl_lane(float x, int src_lane) { return __int_as_float(__builtin_amdgcn_ds_bpermute(src_lane << 2, __float_as_int(x))); }
; __device__ __forceinline__ float ex2(float x) { return __builtin_amdgcn_exp2f(x); }
; __device__ __forceinline__ void sb_item(KParams p, int tb, int hd) {
;     ...
;       for (int T = 7; T >= 0; --T) {
;         if (T <= thi) {
;           const float x = (l1[T][0] + l1[T][1]) + (l1[T][2] + l1[T][3]);
;           float a = shfl_lane(x, (lane + 16) & 63); a = (g < 3) ? a : 0.f;
;           const float y1 = x + a;
;           float b2 = shfl_lane(y1, (lane + 32) & 63); b2 = (g < 2) ? b2 : 0.f;
;           const float incl = y1 + b2;
;           const float tt = shfl_lane(incl, fr);
;           float base = running + (incl - x);
;           const float w3 = ex2(s[T][3] + base); base += l1[T][3];
;           const float w2 = ex2(s[T][2] + base); base += l1[T][2];
;           const float w1 = ex2(s[T][1] + base); base += l1[T][1];
;           const float w0 = ex2(s[T][0] + base);
;           set_pf(pf, T, w0, w1, w2, w3);
;           running += tt;
;         }
;       }
	v_cndmask_b32_e64 v97, v105, 0, s[4:5]
	v_add_f32_e32 v119, v210, v97
	ds_bpermute_b32 v105, v179, v119
	v_cvt_pk_bf16_f32 v97, v84, v83
	v_fma_f32 v83, v111, s92, -v209
	v_exp_f32_e32 v96, v96
	v_max_f32_e32 v190, 0, v104
	s_waitcnt lgkmcnt(0)
	v_cndmask_b32_e64 v185, 0, v105, s[6:7]
	v_pk_add_f32 v[118:119], v[118:119], v[184:185]
	v_max_f32_e32 v202, 0, v168
	v_pk_add_f32 v[210:211], v[118:119], v[210:211] op_sel:[1,0] op_sel_hi:[0,1] neg_lo:[0,1] neg_hi:[0,1]
	v_pk_add_f32 v[210:211], v[118:119], v[210:211]
	v_max_f32_e32 v191, 0, v106
	v_add_f32_e32 v83, v83, v210
	v_mov_b32_e32 v111, v210
	v_mov_b32_e32 v210, v187
	v_mov_b32_e32 v211, v209
	v_pk_add_f32 v[110:111], v[110:111], v[210:211] neg_lo:[0,1] neg_hi:[0,1]
	v_mov_b32_e32 v209, v187
	v_mov_b32_e32 v207, v111
	v_add_f32_e32 v84, v110, v111
	v_pk_add_f32 v[110:111], v[206:207], v[208:209] neg_lo:[0,1] neg_hi:[0,1]
	v_mov_b32_e32 v187, v208
	v_add_f32_e32 v91, v110, v111
	v_mov_b32_e32 v109, v111
	v_pk_add_f32 v[110:111], v[190:191], v[200:201]
	v_pk_add_f32 v[190:191], v[202:203], v[204:205]
	v_pk_add_f32 v[108:109], v[108:109], v[186:187] neg_lo:[0,1] neg_hi:[0,1]
	v_pk_add_f32 v[200:201], v[190:191], v[110:111] neg_lo:[1,1] neg_hi:[1,1]
	v_max_f32_e32 v94, 0, v98
	v_max_f32_e32 v170, 0, v100
	v_max_f32_e32 v95, 0, v102
	v_cvt_pk_bf16_f32 v96, v96, v101
	v_add_f32_e32 v101, v200, v201
	v_add_f32_e32 v108, v108, v109
	ds_bpermute_b32 v184, v180, v119
	ds_bpermute_b32 v105, v178, v101
	v_exp_f32_e32 v119, v108
	v_pk_add_f32 v[108:109], v[94:95], v[146:147]
	v_pk_add_f32 v[146:147], v[170:171], v[188:189]
	v_exp_f32_e32 v91, v91
	v_pk_add_f32 v[94:95], v[146:147], v[108:109] neg_lo:[1,1] neg_hi:[1,1]
	s_waitcnt lgkmcnt(0)
	v_cndmask_b32_e64 v105, v105, 0, s[4:5]
	v_add_f32_e32 v123, v94, v95
	ds_bpermute_b32 v125, v178, v123
	v_exp_f32_e32 v83, v83
	v_exp_f32_e32 v84, v84
	v_add_f32_e32 v105, v101, v105
	ds_bpermute_b32 v121, v179, v105
	v_cvt_pk_bf16_f32 v94, v119, v91
	s_waitcnt lgkmcnt(1)
	v_cndmask_b32_e64 v91, v125, 0, s[4:5]
	v_add_f32_e32 v91, v123, v91
	v_max_f32_e32 v161, 0, v154
	v_max_f32_e32 v163, 0, v156
	v_max_f32_e32 v160, 0, v158
	v_cvt_pk_bf16_f32 v95, v84, v83
	v_fma_f32 v83, v107, s92, -v191
	ds_bpermute_b32 v107, v179, v91
	v_pk_add_f32 v[160:161], v[160:161], v[166:167]
	v_pk_add_f32 v[162:163], v[162:163], v[164:165]
	s_waitcnt lgkmcnt(1)
	v_cndmask_b32_e64 v84, 0, v121, s[6:7]
	v_pk_add_f32 v[164:165], v[160:161], v[162:163] neg_lo:[1,1] neg_hi:[1,1]
	v_add_f32_e32 v84, v105, v84
	v_mov_b32_e32 v119, v164
	v_mov_b32_e32 v185, v165
	ds_bpermute_b32 v170, v180, v84
	v_sub_f32_e32 v84, v84, v101
	v_pk_add_f32 v[118:119], v[118:119], v[184:185]
	v_fma_f32 v101, v103, s92, -v147
	s_waitcnt lgkmcnt(1)
	v_cndmask_b32_e64 v103, 0, v107, s[6:7]
	v_add_f32_e32 v107, v118, v84
	v_mov_b32_e32 v164, v111
	v_mov_b32_e32 v165, v191
	v_add_f32_e32 v83, v83, v107
	v_pk_add_f32 v[106:107], v[106:107], v[164:165] neg_lo:[0,1] neg_hi:[0,1]
	v_mov_b32_e32 v191, v111
	v_mov_b32_e32 v169, v107
	v_add_f32_e32 v84, v106, v107
	v_pk_add_f32 v[106:107], v[168:169], v[190:191] neg_lo:[0,1] neg_hi:[0,1]
	v_add_f32_e32 v91, v91, v103
	v_fma_f32 v121, v99, s92, -v162
	v_add_f32_e32 v99, v106, v107
	ds_bpermute_b32 v186, v180, v91
	v_sub_f32_e32 v91, v91, v123
	v_exp_f32_e32 v123, v99
	ds_bpermute_b32 v99, v178, v119
	v_mov_b32_e32 v105, v107
	v_mov_b32_e32 v111, v190
	v_pk_add_f32 v[104:105], v[104:105], v[110:111] neg_lo:[0,1] neg_hi:[0,1]
	v_mov_b32_e32 v106, v109
	s_waitcnt lgkmcnt(0)
	v_cndmask_b32_e64 v171, v99, 0, s[4:5]
	v_add_f32_e32 v103, v104, v105
	v_pk_add_f32 v[104:105], v[118:119], v[170:171]
	v_exp_f32_e32 v110, v103
	v_add_f32_e32 v103, v104, v91
	v_mov_b32_e32 v107, v147
	v_add_f32_e32 v91, v101, v103
	v_pk_add_f32 v[102:103], v[102:103], v[106:107] neg_lo:[0,1] neg_hi:[0,1]
	v_mov_b32_e32 v147, v109
	v_mov_b32_e32 v101, v103
	v_add_f32_e32 v99, v102, v103
	v_pk_add_f32 v[100:101], v[100:101], v[146:147] neg_lo:[0,1] neg_hi:[0,1]
	v_exp_f32_e32 v102, v99
	v_add_f32_e32 v99, v100, v101
	v_exp_f32_e32 v103, v99
	v_mov_b32_e32 v99, v101
	v_mov_b32_e32 v109, v146
	v_pk_add_f32 v[98:99], v[98:99], v[108:109] neg_lo:[0,1] neg_hi:[0,1]
	ds_bpermute_b32 v106, v179, v105
	v_add_f32_e32 v98, v98, v99
	v_exp_f32_e32 v91, v91
	v_exp_f32_e32 v98, v98
	v_exp_f32_e32 v83, v83
	v_exp_f32_e32 v84, v84
	s_waitcnt lgkmcnt(0)
	v_cndmask_b32_e64 v187, 0, v106, s[6:7]
	v_cvt_pk_bf16_f32 v98, v98, v103
	v_cvt_pk_bf16_f32 v99, v102, v91
	v_pk_add_f32 v[102:103], v[104:105], v[186:187]
	v_cvt_pk_bf16_f32 v101, v84, v83
	v_sub_f32_e32 v84, v103, v119
	v_pk_add_f32 v[106:107], v[102:103], v[84:85] op_sel_hi:[1,0]
	v_max_f32_e32 v145, 0, v90
	v_add_f32_e32 v83, v121, v106
	v_mov_b32_e32 v159, v106
	v_mov_b32_e32 v106, v160
	v_mov_b32_e32 v107, v162
	v_pk_add_f32 v[106:107], v[158:159], v[106:107] neg_lo:[0,1] neg_hi:[0,1]
	v_max_f32_e32 v149, 0, v136
	v_add_f32_e32 v84, v106, v107
	v_mov_b32_e32 v157, v107
	v_pk_mov_b32 v[106:107], v[162:163], v[160:161] op_sel:[1,0]
	v_max_f32_e32 v144, 0, v92
	v_pk_add_f32 v[106:107], v[156:157], v[106:107] neg_lo:[0,1] neg_hi:[0,1]
	v_pk_add_f32 v[108:109], v[148:149], v[150:151]
	v_add_f32_e32 v91, v106, v107
	v_mov_b32_e32 v155, v107
	v_pk_add_f32 v[106:107], v[144:145], v[152:153]
	v_cvt_pk_bf16_f32 v100, v110, v123
	v_pk_add_f32 v[110:111], v[106:107], v[108:109] neg_lo:[1,1] neg_hi:[1,1]
	v_mov_b32_e32 v162, v161
	ds_bpermute_b32 v104, v180, v103
	v_add_f32_e32 v103, v110, v111
	v_pk_add_f32 v[110:111], v[154:155], v[162:163] neg_lo:[0,1] neg_hi:[0,1]
	v_max_f32_e32 v139, 0, v124
	v_max_f32_e32 v87, 0, v126
	v_max_f32_e32 v138, 0, v88
	ds_bpermute_b32 v105, v178, v103
	v_add_f32_e32 v110, v110, v111
	v_exp_f32_e32 v121, v110
	v_pk_add_f32 v[110:111], v[138:139], v[142:143]
	v_pk_add_f32 v[118:119], v[86:87], v[140:141]
	v_exp_f32_e32 v91, v91
	v_pk_add_f32 v[86:87], v[110:111], v[118:119] neg_lo:[1,1] neg_hi:[1,1]
	s_waitcnt lgkmcnt(0)
; __device__ __forceinline__ float shfl_lane(float x, int src_lane) { return __int_as_float(__builtin_amdgcn_ds_bpermute(src_lane << 2, __float_as_int(x))); }
; __device__ __forceinline__ f32x4 mfma16(bf16x8 a, bf16x8 b, f32x4 c) { return __builtin_amdgcn_mfma_f32_16x16x32_bf16(a, b, c, 0, 0, 0); }
; __device__ __forceinline__ float ex2(float x) { return __builtin_amdgcn_exp2f(x); }
; __device__ __forceinline__ void pv_tiles(f32x4 (&o)[8], const bf16_t* Vts, const bf16x8 (&pf)[4], int fr, int g, int tlo, int thi) {
;   __builtin_amdgcn_s_setprio(1);
; #pragma unroll
;   for (int kc = 0; kc < 4; ++kc) {
;     if (2 * kc + 1 >= tlo && 2 * kc <= thi) {
; #pragma unroll
;       for (int dt = 0; dt < 8; ++dt) {
;         const bf16_t* vp = Vts + (dt * 16 + fr) * LROW + kc * 32 + g * 4;
;         bf16x4 lo = *(const bf16x4*)vp, hi = *(const bf16x4*)(vp + 16);
;         bf16x8 a = __builtin_shufflevector(lo, hi, 0, 1, 2, 3, 4, 5, 6, 7);
;         o[dt] = mfma16(a, pf[kc], o[dt]);
;       }
; __device__ __forceinline__ void sb_item(KParams p, int tb, int hd) {
;     ...
;       for (int T = 7; T >= 0; --T) {
;         if (T <= thi) {
;           const float x = (l1[T][0] + l1[T][1]) + (l1[T][2] + l1[T][3]);
;           float a = shfl_lane(x, (lane + 16) & 63); a = (g < 3) ? a : 0.f;
;           const float y1 = x + a;
;           float b2 = shfl_lane(y1, (lane + 32) & 63); b2 = (g < 2) ? b2 : 0.f;
;           const float incl = y1 + b2;
;           const float tt = shfl_lane(incl, fr);
;           float base = running + (incl - x);
;           const float w3 = ex2(s[T][3] + base); base += l1[T][3];
;           const float w2 = ex2(s[T][2] + base); base += l1[T][2];
;           const float w1 = ex2(s[T][1] + base); base += l1[T][1];
;           const float w0 = ex2(s[T][0] + base);
;           set_pf(pf, T, w0, w1, w2, w3);
;           running += tt;
;         }
;       }
;       carry = running;
;       pv_tiles(o, Vts, pf, fr, g, 0, thi);
	v_cndmask_b32_e64 v105, v105, 0, s[4:5]
	v_add_f32_e32 v125, v86, v87
	ds_bpermute_b32 v127, v178, v125
	v_add_f32_e32 v105, v103, v105
	v_exp_f32_e32 v83, v83
	v_exp_f32_e32 v84, v84
	ds_bpermute_b32 v123, v179, v105
	v_cvt_pk_bf16_f32 v86, v121, v91
	s_waitcnt lgkmcnt(1)
	v_cndmask_b32_e64 v91, v127, 0, s[4:5]
	v_add_f32_e32 v91, v125, v91
	v_max_f32_e32 v131, 0, v82
	v_max_f32_e32 v129, 0, v120
	v_max_f32_e32 v130, 0, v122
	v_cvt_pk_bf16_f32 v87, v84, v83
	v_fma_f32 v83, v93, s92, -v108
	ds_bpermute_b32 v93, v179, v91
	s_waitcnt lgkmcnt(1)
	v_cndmask_b32_e64 v84, 0, v123, s[6:7]
	v_pk_add_f32 v[130:131], v[130:131], v[134:135]
	v_pk_add_f32 v[128:129], v[128:129], v[132:133]
	v_add_f32_e32 v84, v105, v84
	v_pk_add_f32 v[132:133], v[130:131], v[128:129] neg_lo:[1,1] neg_hi:[1,1]
	ds_bpermute_b32 v138, v180, v84
	v_sub_f32_e32 v84, v84, v103
	v_mov_b32_e32 v103, v132
	v_mov_b32_e32 v105, v133
	v_pk_add_f32 v[102:103], v[102:103], v[104:105]
	v_fma_f32 v121, v89, s92, -v118
	s_waitcnt lgkmcnt(1)
	v_cndmask_b32_e64 v89, 0, v93, s[6:7]
	v_add_f32_e32 v93, v102, v84
	v_mov_b32_e32 v104, v106
	v_mov_b32_e32 v105, v108
	v_add_f32_e32 v83, v83, v93
	v_pk_add_f32 v[92:93], v[92:93], v[104:105] neg_lo:[0,1] neg_hi:[0,1]
	v_add_f32_e32 v89, v91, v89
	v_add_f32_e32 v84, v92, v93
	v_mov_b32_e32 v137, v93
	v_pk_mov_b32 v[92:93], v[108:109], v[106:107] op_sel:[1,0]
	v_exp_f32_e32 v123, v84
	v_pk_add_f32 v[92:93], v[136:137], v[92:93] neg_lo:[0,1] neg_hi:[0,1]
	v_mov_b32_e32 v108, v107
	v_add_f32_e32 v84, v92, v93
	ds_bpermute_b32 v92, v178, v103
	v_mov_b32_e32 v91, v93
	v_pk_add_f32 v[90:91], v[90:91], v[108:109] neg_lo:[0,1] neg_hi:[0,1]
	ds_bpermute_b32 v140, v180, v89
	v_sub_f32_e32 v89, v89, v125
	s_waitcnt lgkmcnt(1)
	v_cndmask_b32_e64 v139, v92, 0, s[4:5]
	v_add_f32_e32 v90, v90, v91
	v_pk_add_f32 v[92:93], v[102:103], v[138:139]
	v_exp_f32_e32 v108, v90
	v_add_f32_e32 v89, v92, v89
	v_mov_b32_e32 v90, v110
	v_mov_b32_e32 v91, v118
	v_pk_add_f32 v[104:105], v[88:89], v[90:91] neg_lo:[0,1] neg_hi:[0,1]
	v_pk_mov_b32 v[90:91], v[118:119], v[110:111] op_sel:[1,0]
	v_mov_b32_e32 v127, v105
	v_exp_f32_e32 v83, v83
	v_pk_add_f32 v[90:91], v[126:127], v[90:91] neg_lo:[0,1] neg_hi:[0,1]
	v_mov_b32_e32 v118, v111
	v_mov_b32_e32 v125, v91
	v_pk_add_f32 v[106:107], v[124:125], v[118:119] neg_lo:[0,1] neg_hi:[0,1]
	v_add_f32_e32 v90, v90, v91
	v_add_f32_e32 v88, v106, v107
	v_exp_f32_e32 v88, v88
	v_exp_f32_e32 v90, v90
	v_fma_f32 v91, v85, s92, -v128
	v_cvt_pk_bf16_f32 v85, v123, v83
	ds_bpermute_b32 v83, v179, v93
	v_cvt_pk_bf16_f32 v90, v88, v90
	v_add_f32_e32 v88, v104, v105
	v_exp_f32_e32 v106, v88
	v_add_f32_e32 v88, v121, v89
	s_waitcnt lgkmcnt(0)
	v_cndmask_b32_e64 v141, 0, v83, s[6:7]
	v_exp_f32_e32 v107, v88
	v_pk_add_f32 v[88:89], v[92:93], v[140:141]
	v_mov_b32_e32 v102, v130
	v_sub_f32_e32 v92, v89, v103
	v_pk_add_f32 v[92:93], v[88:89], v[92:93] op_sel_hi:[1,0]
	v_mov_b32_e32 v103, v128
	v_mov_b32_e32 v123, v92
	v_exp_f32_e32 v84, v84
	v_pk_add_f32 v[102:103], v[122:123], v[102:103] neg_lo:[0,1] neg_hi:[0,1]
	v_pk_mov_b32 v[104:105], v[128:129], v[130:131] op_sel:[1,0]
	v_mov_b32_e32 v121, v103
	v_pk_add_f32 v[104:105], v[120:121], v[104:105] neg_lo:[0,1] neg_hi:[0,1]
	v_mov_b32_e32 v128, v131
	v_mov_b32_e32 v83, v105
	v_cvt_pk_bf16_f32 v84, v108, v84
	ds_bpermute_b32 v108, v180, v89
	v_pk_add_f32 v[82:83], v[82:83], v[128:129] neg_lo:[0,1] neg_hi:[0,1]
	v_add_f32_e32 v89, v102, v103
	v_add_f32_e32 v82, v82, v83
	v_add_f32_e32 v83, v104, v105
	v_add_f32_e32 v91, v91, v92
	v_exp_f32_e32 v82, v82
	v_exp_f32_e32 v83, v83
	v_exp_f32_e32 v89, v89
	v_exp_f32_e32 v92, v91
	s_waitcnt lgkmcnt(0)
	v_add_f32_e32 v118, v88, v108
	v_cvt_pk_bf16_f32 v91, v106, v107
	v_cvt_pk_bf16_f32 v88, v82, v83
	v_cvt_pk_bf16_f32 v89, v89, v92
	s_setprio 1
	v_add_u32_e32 v92, 0x8800, v181
	v_add_u32_e32 v93, 0x9800, v181
	v_add_u32_e32 v106, 0xa800, v181
	v_add_u32_e32 v107, 0xb800, v181
	v_add_u32_e32 v108, 0xc800, v181
	v_add_u32_e32 v109, 0xd800, v181
	v_add_u32_e32 v110, 0xe800, v181
	v_add_u32_e32 v111, 0xf800, v181
	ds_read2_b64 v[128:131], v92 offset1:4
	ds_read2_b64 v[132:135], v93 offset0:32 offset1:36
	ds_read2_b64 v[136:139], v106 offset0:64 offset1:68
	ds_read2_b64 v[140:143], v107 offset0:96 offset1:100
	ds_read2_b64 v[144:147], v108 offset0:128 offset1:132
	ds_read2_b64 v[148:151], v109 offset0:160 offset1:164
	ds_read2_b64 v[152:155], v110 offset0:192 offset1:196
	ds_read2_b64 v[156:159], v111 offset0:224 offset1:228
	ds_read2_b64 v[160:163], v92 offset0:8 offset1:12
	ds_read2_b64 v[164:167], v93 offset0:40 offset1:44
	ds_read2_b64 v[168:171], v106 offset0:72 offset1:76
	ds_read2_b64 v[188:191], v107 offset0:104 offset1:108
	s_waitcnt lgkmcnt(11)
; __device__ __forceinline__ f32x4 mfma16(bf16x8 a, bf16x8 b, f32x4 c) { return __builtin_amdgcn_mfma_f32_16x16x32_bf16(a, b, c, 0, 0, 0); }
; __device__ __forceinline__ void pv_tiles(f32x4 (&o)[8], const bf16_t* Vts, const bf16x8 (&pf)[4], int fr, int g, int tlo, int thi) {
;   __builtin_amdgcn_s_setprio(1);
; #pragma unroll
;   for (int kc = 0; kc < 4; ++kc) {
;     if (2 * kc + 1 >= tlo && 2 * kc <= thi) {
; #pragma unroll
;       for (int dt = 0; dt < 8; ++dt) {
;         const bf16_t* vp = Vts + (dt * 16 + fr) * LROW + kc * 32 + g * 4;
;         bf16x4 lo = *(const bf16x4*)vp, hi = *(const bf16x4*)(vp + 16);
;         bf16x8 a = __builtin_shufflevector(lo, hi, 0, 1, 2, 3, 4, 5, 6, 7);
;         o[dt] = mfma16(a, pf[kc], o[dt]);
;       }
;     }
;   }
;   __builtin_amdgcn_s_setprio(0);
; }
	v_mfma_f32_16x16x32_bf16 v[78:81], v[128:131], v[88:91], v[78:81]
	ds_read2_b64 v[128:131], v108 offset0:136 offset1:140
	s_waitcnt lgkmcnt(11)
	v_mfma_f32_16x16x32_bf16 v[74:77], v[132:135], v[88:91], v[74:77]
	ds_read2_b64 v[132:135], v109 offset0:168 offset1:172
	s_waitcnt lgkmcnt(11)
	v_mfma_f32_16x16x32_bf16 v[70:73], v[136:139], v[88:91], v[70:73]
	ds_read2_b64 v[136:139], v110 offset0:200 offset1:204
	s_waitcnt lgkmcnt(11)
	v_mfma_f32_16x16x32_bf16 v[66:69], v[140:143], v[88:91], v[66:69]
	ds_read2_b64 v[140:143], v111 offset0:232 offset1:236
	s_waitcnt lgkmcnt(11)
	v_mfma_f32_16x16x32_bf16 v[62:65], v[144:147], v[88:91], v[62:65]
	ds_read2_b64 v[144:147], v92 offset0:16 offset1:20
	s_waitcnt lgkmcnt(11)
	v_mfma_f32_16x16x32_bf16 v[58:61], v[148:151], v[88:91], v[58:61]
	ds_read2_b64 v[148:151], v93 offset0:48 offset1:52
	s_waitcnt lgkmcnt(11)
	v_mfma_f32_16x16x32_bf16 v[54:57], v[152:155], v[88:91], v[54:57]
	ds_read2_b64 v[152:155], v106 offset0:80 offset1:84
	s_waitcnt lgkmcnt(11)
	v_mfma_f32_16x16x32_bf16 v[50:53], v[156:159], v[88:91], v[50:53]
	ds_read2_b64 v[156:159], v107 offset0:112 offset1:116
	s_waitcnt lgkmcnt(11)
	v_mfma_f32_16x16x32_bf16 v[78:81], v[160:163], v[84:87], v[78:81]
	ds_read2_b64 v[160:163], v108 offset0:144 offset1:148
	s_waitcnt lgkmcnt(11)
	v_mfma_f32_16x16x32_bf16 v[74:77], v[164:167], v[84:87], v[74:77]
	ds_read2_b64 v[164:167], v109 offset0:176 offset1:180
	s_waitcnt lgkmcnt(11)
	v_mfma_f32_16x16x32_bf16 v[70:73], v[168:171], v[84:87], v[70:73]
	ds_read2_b64 v[168:171], v110 offset0:208 offset1:212
	s_waitcnt lgkmcnt(11)
	v_mfma_f32_16x16x32_bf16 v[66:69], v[188:191], v[84:87], v[66:69]
	ds_read2_b64 v[188:191], v111 offset0:240 offset1:244
	s_waitcnt lgkmcnt(11)
	v_mfma_f32_16x16x32_bf16 v[62:65], v[128:131], v[84:87], v[62:65]
	ds_read2_b64 v[128:131], v92 offset0:24 offset1:28
	s_waitcnt lgkmcnt(11)
	v_mfma_f32_16x16x32_bf16 v[58:61], v[132:135], v[84:87], v[58:61]
	ds_read2_b64 v[132:135], v93 offset0:56 offset1:60
	s_waitcnt lgkmcnt(11)
	v_mfma_f32_16x16x32_bf16 v[54:57], v[136:139], v[84:87], v[54:57]
	ds_read2_b64 v[136:139], v106 offset0:88 offset1:92
	s_waitcnt lgkmcnt(11)
	v_mfma_f32_16x16x32_bf16 v[50:53], v[140:143], v[84:87], v[50:53]
	ds_read2_b64 v[140:143], v107 offset0:120 offset1:124
	s_waitcnt lgkmcnt(11)
	v_mfma_f32_16x16x32_bf16 v[78:81], v[144:147], v[98:101], v[78:81]
	ds_read2_b64 v[144:147], v108 offset0:152 offset1:156
	s_waitcnt lgkmcnt(11)
	v_mfma_f32_16x16x32_bf16 v[74:77], v[148:151], v[98:101], v[74:77]
	ds_read2_b64 v[148:151], v109 offset0:184 offset1:188
	s_waitcnt lgkmcnt(11)
	v_mfma_f32_16x16x32_bf16 v[70:73], v[152:155], v[98:101], v[70:73]
	ds_read2_b64 v[152:155], v110 offset0:216 offset1:220
	s_waitcnt lgkmcnt(11)
	v_mfma_f32_16x16x32_bf16 v[66:69], v[156:159], v[98:101], v[66:69]
	ds_read2_b64 v[156:159], v111 offset0:248 offset1:252
	s_waitcnt lgkmcnt(11)
	v_mfma_f32_16x16x32_bf16 v[62:65], v[160:163], v[98:101], v[62:65]
	s_waitcnt lgkmcnt(10)
	v_mfma_f32_16x16x32_bf16 v[58:61], v[164:167], v[98:101], v[58:61]
	s_waitcnt lgkmcnt(9)
	v_mfma_f32_16x16x32_bf16 v[54:57], v[168:171], v[98:101], v[54:57]
	s_waitcnt lgkmcnt(8)
	v_mfma_f32_16x16x32_bf16 v[50:53], v[188:191], v[98:101], v[50:53]
	s_waitcnt lgkmcnt(7)
	v_mfma_f32_16x16x32_bf16 v[78:81], v[128:131], v[94:97], v[78:81]
	s_waitcnt lgkmcnt(6)
	v_mfma_f32_16x16x32_bf16 v[74:77], v[132:135], v[94:97], v[74:77]
	s_waitcnt lgkmcnt(5)
	v_mfma_f32_16x16x32_bf16 v[70:73], v[136:139], v[94:97], v[70:73]
	s_waitcnt lgkmcnt(4)
	v_mfma_f32_16x16x32_bf16 v[66:69], v[140:143], v[94:97], v[66:69]
	s_waitcnt lgkmcnt(3)
	v_mfma_f32_16x16x32_bf16 v[62:65], v[144:147], v[94:97], v[62:65]
	s_waitcnt lgkmcnt(2)
	v_mfma_f32_16x16x32_bf16 v[58:61], v[148:151], v[94:97], v[58:61]
	s_waitcnt lgkmcnt(1)
	v_mfma_f32_16x16x32_bf16 v[54:57], v[152:155], v[94:97], v[54:57]
	s_waitcnt lgkmcnt(0)
	v_mfma_f32_16x16x32_bf16 v[50:53], v[156:159], v[94:97], v[50:53]
	s_setprio 0
